# MLA prefetch addresses: SGPR base + 32-bit lane offset instead of 64-bit VALU address math
# baseline (speedup 1.0000x reference)
; template <int DQK, bool NA, bool SMAX, int LDV> ...
;     ...
;     if (it + 2 < nkt) {
;       const int kb = (it + 2) * 64 + ((it + 2) >= 4 ? koff : 0);
; #pragma unroll
;       for (int i = 0; i < NKC; ++i) rk_ld[i] = *(const u32x4*)(Kp + (size_t)(kb + kkey[i]) * ldk + kcc[i] * 8);
;       rv_ld = *(const u32x4*)(Vp + (size_t)(kb + vdv) * LDV + vcc * 8);
;     }
.LBB0_1136:
	s_cmp_lt_u32 s19, 34
	s_cselect_b64 s[26:27], -1, 0
	s_cmp_gt_u32 s19, 33
	s_cselect_b64 s[4:5], -1, 0
	s_and_b64 vcc, exec, s[4:5]
	s_cbranch_vccnz .LBB0_1138
	s_add_u32 s100, s20, 0x1094d000
	s_addc_u32 s101, s21, 0
	global_load_dwordx4 v[40:43], v126, s[100:101]
	global_load_dwordx4 v[44:47], v124, s[100:101]
	s_nop 2
	s_add_u32 s100, s20, 0x1243d000
	s_addc_u32 s101, s21, 0
	global_load_dwordx4 v[52:55], v120, s[100:101]

; template <int DQK, bool NA, bool SMAX, int LDV> ...
;     ...
;     if (it + 2 < nkt) {
;       const int kb = (it + 2) * 64 + ((it + 2) >= 4 ? koff : 0);
; #pragma unroll
;       for (int i = 0; i < NKC; ++i) rk_ld[i] = *(const u32x4*)(Kp + (size_t)(kb + kkey[i]) * ldk + kcc[i] * 8);
;       rv_ld = *(const u32x4*)(Vp + (size_t)(kb + vdv) * LDV + vcc * 8);
;     }
;     ...
;     if (more) {
;       char* nx = smem + (cur ^ 1) * STG;
; #pragma unroll
;       for (int i = 0; i < NKC; ++i) if (kval[i]) *(u32x4*)(nx + kkey[i] * KSTR + kcc[i] * 16) = rk_wr[i];
;       *(u32x4*)(nx + KBYTES + vdv * VSTR + vcc * 16) = rv_wr;
;     }
;     __syncthreads();
.LBB0_1142:
	s_or_b64 exec, exec, s[42:43]
	s_cmp_gt_u32 s19, 32
	s_waitcnt vmcnt(0)
	ds_write_b128 v173, v[60:63] offset:38912
	s_waitcnt lgkmcnt(0)
	s_barrier
	s_cbranch_scc1 .LBB0_1144
	s_add_u32 s100, s20, 0x10965000
	s_addc_u32 s101, s21, 0
	global_load_dwordx4 v[48:51], v126, s[100:101]
	global_load_dwordx4 v[56:59], v124, s[100:101]
	s_nop 2
	s_add_u32 s100, s20, 0x1244d000
	s_addc_u32 s101, s21, 0
	global_load_dwordx4 v[60:63], v120, s[100:101]
